# code placement: only the P4 K-loop head moved to the byte phase it has in the baseline (32 mod 64, 0 mod 8); P1 loop unchanged
# speedup vs baseline: 1.0028x; 1.0028x over previous
; template <class Epi, class Sched, bool ALIGN_EPI = false, bool SP2 = false>
; __device__ __forceinline__ void gemm_phase(PG8_LAS unsigned char* lds, const Gemm g, const Sched& S, const Epi& E) {
;     ...
;         const bool has_next = S.next(ui + 1, nxt);
;         const char* nA = has_next ? (const char*)g.A + (size_t)nxt.pm * tstep : cA; const char* nB = has_next ? (const char*)g.Bt + (size_t)nxt.pn * tstep : cB;
;         for (int t = 0; t < nt; t += 2) {
;             const bool last = (t == nt - 2);
;             const char* a1 = cA + (size_t)(t + 1) * kstep;
;             const char* a2 = last ? nA : cA + (size_t)(t + 2) * kstep; const char* b2 = last ? nB : cB + (size_t)(t + 2) * kstep;
;     ...
; #pragma unroll
;         for (int a = 0; a < 2; ++a)
; #pragma unroll
;             for (int b = 0; b < 2; ++b)
; #pragma unroll
;                 for (int m = 0; m < 4; ++m)
; #pragma unroll
;                     for (int n = 0; n < 2; ++n) acc[a][b][m][n] = (f32x4){0.f, 0.f, 0.f, 0.f};
.LBB0_456:
	s_ashr_i32 s25, s24, 31
	s_lshl_b64 s[26:27], s[24:25], 19
	s_add_u32 s26, s33, s26
	s_addc_u32 s27, s42, s27
	s_and_b64 s[28:29], s[0:1], exec
	s_cselect_b32 s25, s27, s35
	s_cselect_b32 s61, s26, s34
	s_ashr_i32 s21, s20, 31
	s_lshl_b64 s[28:29], s[20:21], 19
	s_add_u32 s28, s43, s28
	s_addc_u32 s29, s44, s29
	s_and_b64 s[38:39], s[0:1], exec
	s_cselect_b32 s21, s29, s41
	s_cselect_b32 s62, s28, s40
	s_add_u32 s34, s34, 0x40080
	s_addc_u32 s35, s35, 0
	s_add_u32 s63, s40, 0x100
	v_mov_b32_e32 v0, 0
	s_addc_u32 s64, s41, 0
	s_mov_b32 s65, -2
	v_mov_b32_e32 v1, v0
	s_cmp_lg_u32 s51, 1
	s_cbranch_scc1 .Lp4_peel
	v_mov_b32_e32 v2, v0
	v_mov_b32_e32 v3, v0
	v_mov_b32_e32 v4, v0
	v_mov_b32_e32 v5, v0
	v_mov_b32_e32 v6, v0
	v_mov_b32_e32 v7, v0
	v_mov_b32_e32 v8, v0
	v_mov_b32_e32 v9, v0
	v_mov_b32_e32 v10, v0
	v_mov_b32_e32 v11, v0
	v_mov_b32_e32 v16, v0
	v_mov_b32_e32 v17, v0
	v_mov_b32_e32 v18, v0
	v_mov_b32_e32 v19, v0
	v_mov_b32_e32 v28, v0
	v_mov_b32_e32 v29, v0
	v_mov_b32_e32 v30, v0
	v_mov_b32_e32 v31, v0
	v_mov_b32_e32 v32, v0
	v_mov_b32_e32 v33, v0
	v_mov_b32_e32 v34, v0
	v_mov_b32_e32 v35, v0
	v_mov_b32_e32 v40, v0
	v_mov_b32_e32 v41, v0
	v_mov_b32_e32 v42, v0
	v_mov_b32_e32 v43, v0
	v_mov_b32_e32 v44, v0
	v_mov_b32_e32 v45, v0
	v_mov_b32_e32 v46, v0
	v_mov_b32_e32 v47, v0
	v_mov_b32_e32 v12, v0
	v_mov_b32_e32 v13, v0
	v_mov_b32_e32 v14, v0
	v_mov_b32_e32 v15, v0
	v_mov_b32_e32 v20, v0
	v_mov_b32_e32 v21, v0
	v_mov_b32_e32 v22, v0
	v_mov_b32_e32 v23, v0
	v_mov_b32_e32 v24, v0
	v_mov_b32_e32 v25, v0
	v_mov_b32_e32 v26, v0
	v_mov_b32_e32 v27, v0
	v_mov_b32_e32 v36, v0
	v_mov_b32_e32 v37, v0
	v_mov_b32_e32 v38, v0
	v_mov_b32_e32 v39, v0
	v_mov_b32_e32 v48, v0
	v_mov_b32_e32 v49, v0
	v_mov_b32_e32 v50, v0
	v_mov_b32_e32 v51, v0
	v_mov_b32_e32 v52, v0
	v_mov_b32_e32 v53, v0
	v_mov_b32_e32 v54, v0
	v_mov_b32_e32 v55, v0
	v_mov_b32_e32 v56, v0
	v_mov_b32_e32 v57, v0
	v_mov_b32_e32 v58, v0
	v_mov_b32_e32 v59, v0
	v_mov_b32_e32 v60, v0
	v_mov_b32_e32 v61, v0
	v_mov_b32_e32 v62, v0
	v_mov_b32_e32 v63, v0
	v_mov_b32_e32 v64, v0
	v_mov_b32_e32 v65, v0
	v_mov_b32_e32 v66, v0
	v_mov_b32_e32 v67, v0
	v_mov_b32_e32 v68, v0
	v_mov_b32_e32 v69, v0
	v_mov_b32_e32 v70, v0
	v_mov_b32_e32 v71, v0
	v_mov_b32_e32 v72, v0
	v_mov_b32_e32 v73, v0
	v_mov_b32_e32 v74, v0
	v_mov_b32_e32 v75, v0
	v_mov_b32_e32 v80, v0
	v_mov_b32_e32 v81, v0
	v_mov_b32_e32 v82, v0
	v_mov_b32_e32 v83, v0
	v_mov_b32_e32 v92, v0
	v_mov_b32_e32 v93, v0
	v_mov_b32_e32 v94, v0
	v_mov_b32_e32 v95, v0
	v_mov_b32_e32 v100, v0
	v_mov_b32_e32 v101, v0
	v_mov_b32_e32 v102, v0
	v_mov_b32_e32 v103, v0
	v_mov_b32_e32 v104, v0
	v_mov_b32_e32 v105, v0
	v_mov_b32_e32 v106, v0
	v_mov_b32_e32 v107, v0
	v_mov_b32_e32 v108, v0
	v_mov_b32_e32 v109, v0
	v_mov_b32_e32 v110, v0
	v_mov_b32_e32 v111, v0
	v_mov_b32_e32 v76, v0
	v_mov_b32_e32 v77, v0
	v_mov_b32_e32 v78, v0
	v_mov_b32_e32 v79, v0
	v_mov_b32_e32 v84, v0
	v_mov_b32_e32 v85, v0
	v_mov_b32_e32 v86, v0
	v_mov_b32_e32 v87, v0
	v_mov_b32_e32 v88, v0
	v_mov_b32_e32 v89, v0
	v_mov_b32_e32 v90, v0
	v_mov_b32_e32 v91, v0
	v_mov_b32_e32 v96, v0
	v_mov_b32_e32 v97, v0
	v_mov_b32_e32 v98, v0
	v_mov_b32_e32 v99, v0
	v_mov_b32_e32 v112, v0
	v_mov_b32_e32 v113, v0
	v_mov_b32_e32 v114, v0
	v_mov_b32_e32 v115, v0
	v_mov_b32_e32 v116, v0
	v_mov_b32_e32 v117, v0
	v_mov_b32_e32 v118, v0
	v_mov_b32_e32 v119, v0
	v_mov_b32_e32 v120, v0
	v_mov_b32_e32 v121, v0
	v_mov_b32_e32 v122, v0
	v_mov_b32_e32 v123, v0
	v_mov_b32_e32 v124, v0
	v_mov_b32_e32 v125, v0
	v_mov_b32_e32 v126, v0
	v_mov_b32_e32 v127, v0
	.p2align	6
	s_nop 0
	s_nop 0
	s_nop 0
	s_nop 0
	s_nop 0
	s_nop 0
	s_nop 0
	s_nop 0
